# attention PV section: first two V-tile ds_read_b128 issued early (behind the last softmax read of their destination registers) so the LDS latency overlaps the exp/cvt block; code size unchanged
# speedup vs baseline: 1.0090x; 1.0003x over previous
; __device__ __forceinline__ void attn_item(const Params& p, unsigned char* lds, int item) {
;     ...
;             { const unsigned char* va = lds + AT_V + qi * 528 + 64 * ch + 16 * g4;
; #pragma unroll
;               for (int dt = 0; dt < 8; ++dt) { const bf16x8 a = *(const bf16x8*)(va + dt * 16 * 528);
;                   otA[dt] = __builtin_amdgcn_mfma_f32_16x16x32_bf16(a, pbA, otA[dt], 0, 0, 0); otB[dt] = __builtin_amdgcn_mfma_f32_16x16x32_bf16(a, pbB, otB[dt], 0, 0, 0); } }
.LBB0_424:
	v_sub_f32_e32 v134, v145, v132
	v_exp_f32_e32 v138, v134
	v_sub_f32_e32 v134, v146, v132
	v_exp_f32_e32 v139, v134
	v_sub_f32_e32 v134, v147, v132
	v_exp_f32_e32 v192, v134
	v_sub_f32_e32 v134, v188, v132
	v_sub_f32_e32 v2, v2, v132
	v_sub_f32_e32 v3, v3, v132
	v_sub_f32_e32 v133, v144, v132
	ds_read_b128 v[144:147], v205 offset:64
	ds_read_b128 v[248:251], v205 offset:8512
	v_exp_f32_e32 v188, v134
	v_sub_f32_e32 v134, v189, v132
	v_exp_f32_e32 v2, v2
	v_exp_f32_e32 v3, v3
	v_exp_f32_e32 v133, v133
	v_exp_f32_e32 v189, v134
	v_cvt_pk_bf16_f32 v134, v2, v3
	v_cvt_pk_bf16_f32 v135, v133, v138
	v_cvt_pk_bf16_f32 v136, v139, v192
	v_cvt_pk_bf16_f32 v137, v188, v189
	s_waitcnt lgkmcnt(1)
	v_mfma_f32_16x16x32_bf16 v[128:131], v[144:147], v[140:143], v[128:131]
	v_add_f32_e32 v183, v246, v183
	v_add_f32_e32 v183, v241, v183
	v_add_f32_e32 v183, v243, v183
	v_mfma_f32_16x16x32_bf16 v[96:99], v[144:147], v[134:137], v[96:99]
	v_add_f32_e32 v183, v244, v183
	v_add_f32_e32 v183, v245, v183
	v_add_f32_e32 v183, v247, v183
	s_waitcnt lgkmcnt(0)
	v_mfma_f32_16x16x32_bf16 v[124:127], v[248:251], v[140:143], v[124:127]
	v_add_f32_e32 v2, v2, v239
	v_add_f32_e32 v2, v3, v2
	v_add_f32_e32 v2, v133, v2
	v_mfma_f32_16x16x32_bf16 v[92:95], v[248:251], v[134:137], v[92:95]
	ds_read_b128 v[144:147], v205 offset:16960
	ds_read_b128 v[248:251], v205 offset:25408
	v_add_f32_e32 v2, v138, v2
	v_add_f32_e32 v2, v139, v2
	s_waitcnt lgkmcnt(1)
	v_mfma_f32_16x16x32_bf16 v[120:123], v[144:147], v[140:143], v[120:123]
	v_add_f32_e32 v2, v192, v2
	v_add_f32_e32 v183, v190, v183
	v_add_f32_e32 v2, v188, v2
	v_mfma_f32_16x16x32_bf16 v[88:91], v[144:147], v[134:137], v[88:91]
	v_add_f32_e32 v183, v191, v183
	v_add_f32_e32 v239, v189, v2
	s_waitcnt lgkmcnt(0)
	v_mfma_f32_16x16x32_bf16 v[116:119], v[248:251], v[140:143], v[116:119]
	v_mfma_f32_16x16x32_bf16 v[84:87], v[248:251], v[134:137], v[84:87]
	ds_read_b128 v[144:147], v205 offset:33856
	ds_read_b128 v[248:251], v205 offset:42304
	ds_read_b128 v[244:247], v205 offset:59200
	s_waitcnt lgkmcnt(2)
	v_mfma_f32_16x16x32_bf16 v[112:115], v[144:147], v[140:143], v[112:115]
	v_mfma_f32_16x16x32_bf16 v[80:83], v[144:147], v[134:137], v[80:83]
	ds_read_b128 v[144:147], v205 offset:50752
	s_waitcnt lgkmcnt(2)
	v_mfma_f32_16x16x32_bf16 v[100:103], v[248:251], v[140:143], v[100:103]
	v_mfma_f32_16x16x32_bf16 v[68:71], v[248:251], v[134:137], v[68:71]
	s_waitcnt lgkmcnt(0)
	v_mfma_f32_16x16x32_bf16 v[108:111], v[144:147], v[140:143], v[108:111]
	v_mfma_f32_16x16x32_bf16 v[76:79], v[144:147], v[134:137], v[76:79]
	v_mfma_f32_16x16x32_bf16 v[104:107], v[244:247], v[140:143], v[104:107]
	v_mfma_f32_16x16x32_bf16 v[72:75], v[244:247], v[134:137], v[72:75]
	v_mov_b32_e32 v240, v132
	v_mov_b32_e32 v241, v242
	s_or_b64 exec, exec, s[10:11]
	v_cmp_lt_u32_e32 vcc, 4, v171
	s_and_saveexec_b64 s[10:11], vcc
	s_cbranch_execz .LBB0_401

; __device__ __forceinline__ void attn_item(const Params& p, unsigned char* lds, int item) {
;     ...
;             { const unsigned char* va = lds + AT_V + qi * 528 + 64 * ch + 16 * g4;
; #pragma unroll
;               for (int dt = 0; dt < 8; ++dt) { const bf16x8 a = *(const bf16x8*)(va + dt * 16 * 528);
;                   otA[dt] = __builtin_amdgcn_mfma_f32_16x16x32_bf16(a, pbA, otA[dt], 0, 0, 0); otB[dt] = __builtin_amdgcn_mfma_f32_16x16x32_bf16(a, pbB, otB[dt], 0, 0, 0); } }
.LBB0_443:
	v_sub_f32_e32 v134, v145, v132
	v_exp_f32_e32 v138, v134
	v_sub_f32_e32 v134, v146, v132
	v_exp_f32_e32 v139, v134
	v_sub_f32_e32 v134, v147, v132
	v_exp_f32_e32 v192, v134
	v_sub_f32_e32 v134, v188, v132
	v_sub_f32_e32 v2, v2, v132
	v_sub_f32_e32 v3, v3, v132
	v_sub_f32_e32 v133, v144, v132
	ds_read_b128 v[144:147], v205 offset:128
	ds_read_b128 v[248:251], v205 offset:8576
	v_exp_f32_e32 v188, v134
	v_sub_f32_e32 v134, v189, v132
	v_exp_f32_e32 v2, v2
	v_exp_f32_e32 v3, v3
	v_exp_f32_e32 v133, v133
	v_exp_f32_e32 v189, v134
	v_cvt_pk_bf16_f32 v134, v2, v3
	v_cvt_pk_bf16_f32 v135, v133, v138
	v_cvt_pk_bf16_f32 v136, v139, v192
	v_cvt_pk_bf16_f32 v137, v188, v189
	s_waitcnt lgkmcnt(1)
	v_mfma_f32_16x16x32_bf16 v[128:131], v[144:147], v[140:143], v[128:131]
	v_add_f32_e32 v183, v246, v183
	v_add_f32_e32 v183, v241, v183
	v_add_f32_e32 v183, v243, v183
	v_mfma_f32_16x16x32_bf16 v[96:99], v[144:147], v[134:137], v[96:99]
	v_add_f32_e32 v183, v244, v183
	v_add_f32_e32 v183, v245, v183
	v_add_f32_e32 v183, v247, v183
	s_waitcnt lgkmcnt(0)
	v_mfma_f32_16x16x32_bf16 v[124:127], v[248:251], v[140:143], v[124:127]
	v_add_f32_e32 v2, v2, v239
	v_add_f32_e32 v2, v3, v2
	v_add_f32_e32 v2, v133, v2
	v_mfma_f32_16x16x32_bf16 v[92:95], v[248:251], v[134:137], v[92:95]
	ds_read_b128 v[144:147], v205 offset:17024
	ds_read_b128 v[248:251], v205 offset:25472
	v_add_f32_e32 v2, v138, v2
	v_add_f32_e32 v2, v139, v2
	s_waitcnt lgkmcnt(1)
	v_mfma_f32_16x16x32_bf16 v[120:123], v[144:147], v[140:143], v[120:123]
	v_add_f32_e32 v2, v192, v2
	v_add_f32_e32 v183, v190, v183
	v_add_f32_e32 v2, v188, v2
	v_mfma_f32_16x16x32_bf16 v[88:91], v[144:147], v[134:137], v[88:91]
	v_add_f32_e32 v183, v191, v183
	v_add_f32_e32 v239, v189, v2
	s_waitcnt lgkmcnt(0)
	v_mfma_f32_16x16x32_bf16 v[116:119], v[248:251], v[140:143], v[116:119]
	v_mfma_f32_16x16x32_bf16 v[84:87], v[248:251], v[134:137], v[84:87]
	ds_read_b128 v[144:147], v205 offset:33920
	ds_read_b128 v[248:251], v205 offset:42368
	ds_read_b128 v[244:247], v205 offset:59264
	s_waitcnt lgkmcnt(2)
	v_mfma_f32_16x16x32_bf16 v[112:115], v[144:147], v[140:143], v[112:115]
	v_mfma_f32_16x16x32_bf16 v[80:83], v[144:147], v[134:137], v[80:83]
	ds_read_b128 v[144:147], v205 offset:50816
	s_waitcnt lgkmcnt(2)
	v_mfma_f32_16x16x32_bf16 v[100:103], v[248:251], v[140:143], v[100:103]
	v_mfma_f32_16x16x32_bf16 v[68:71], v[248:251], v[134:137], v[68:71]
	s_waitcnt lgkmcnt(0)
	v_mfma_f32_16x16x32_bf16 v[108:111], v[144:147], v[140:143], v[108:111]
	v_mfma_f32_16x16x32_bf16 v[76:79], v[144:147], v[134:137], v[76:79]
	v_mfma_f32_16x16x32_bf16 v[104:107], v[244:247], v[140:143], v[104:107]
	v_mfma_f32_16x16x32_bf16 v[72:75], v[244:247], v[134:137], v[72:75]
	v_mov_b32_e32 v240, v132
	v_mov_b32_e32 v241, v242
	s_or_b64 exec, exec, s[10:11]
	v_cmp_lt_u32_e32 vcc, 6, v171
	s_and_saveexec_b64 s[10:11], vcc
	s_cbranch_execz .LBB0_402

; __device__ __forceinline__ void attn_item(const Params& p, unsigned char* lds, int item) {
;     ...
;             { const unsigned char* va = lds + AT_V + qi * 528 + 64 * ch + 16 * g4;
; #pragma unroll
;               for (int dt = 0; dt < 8; ++dt) { const bf16x8 a = *(const bf16x8*)(va + dt * 16 * 528);
;                   otA[dt] = __builtin_amdgcn_mfma_f32_16x16x32_bf16(a, pbA, otA[dt], 0, 0, 0); otB[dt] = __builtin_amdgcn_mfma_f32_16x16x32_bf16(a, pbB, otB[dt], 0, 0, 0); } }
.LBB0_462:
	v_sub_f32_e32 v134, v145, v132
	v_exp_f32_e32 v138, v134
	v_sub_f32_e32 v134, v146, v132
	v_exp_f32_e32 v139, v134
	v_sub_f32_e32 v134, v147, v132
	v_exp_f32_e32 v192, v134
	v_sub_f32_e32 v134, v188, v132
	v_sub_f32_e32 v2, v2, v132
	v_sub_f32_e32 v3, v3, v132
	v_sub_f32_e32 v133, v144, v132
	ds_read_b128 v[144:147], v205 offset:192
	ds_read_b128 v[248:251], v205 offset:8640
	v_exp_f32_e32 v188, v134
	v_sub_f32_e32 v134, v189, v132
	v_exp_f32_e32 v2, v2
	v_exp_f32_e32 v3, v3
	v_exp_f32_e32 v133, v133
	v_exp_f32_e32 v189, v134
	v_cvt_pk_bf16_f32 v134, v2, v3
	v_cvt_pk_bf16_f32 v135, v133, v138
	v_cvt_pk_bf16_f32 v136, v139, v192
	v_cvt_pk_bf16_f32 v137, v188, v189
	s_waitcnt lgkmcnt(1)
	v_mfma_f32_16x16x32_bf16 v[128:131], v[144:147], v[140:143], v[128:131]
	v_add_f32_e32 v183, v246, v183
	v_add_f32_e32 v183, v241, v183
	v_add_f32_e32 v183, v243, v183
	v_mfma_f32_16x16x32_bf16 v[96:99], v[144:147], v[134:137], v[96:99]
	v_add_f32_e32 v183, v244, v183
	v_add_f32_e32 v183, v245, v183
	v_add_f32_e32 v183, v247, v183
	s_waitcnt lgkmcnt(0)
	v_mfma_f32_16x16x32_bf16 v[124:127], v[248:251], v[140:143], v[124:127]
	v_add_f32_e32 v2, v2, v239
	v_add_f32_e32 v2, v3, v2
	v_add_f32_e32 v2, v133, v2
	v_mfma_f32_16x16x32_bf16 v[92:95], v[248:251], v[134:137], v[92:95]
	ds_read_b128 v[144:147], v205 offset:17088
	ds_read_b128 v[248:251], v205 offset:25536
	v_add_f32_e32 v2, v138, v2
	v_add_f32_e32 v2, v139, v2
	s_waitcnt lgkmcnt(1)
	v_mfma_f32_16x16x32_bf16 v[120:123], v[144:147], v[140:143], v[120:123]
	v_add_f32_e32 v2, v192, v2
	v_add_f32_e32 v183, v190, v183
	v_add_f32_e32 v2, v188, v2
	v_mfma_f32_16x16x32_bf16 v[88:91], v[144:147], v[134:137], v[88:91]
	v_add_f32_e32 v183, v191, v183
	v_add_f32_e32 v239, v189, v2
	s_waitcnt lgkmcnt(0)
	v_mfma_f32_16x16x32_bf16 v[116:119], v[248:251], v[140:143], v[116:119]
	v_mfma_f32_16x16x32_bf16 v[84:87], v[248:251], v[134:137], v[84:87]
	ds_read_b128 v[144:147], v205 offset:33984
	ds_read_b128 v[248:251], v205 offset:42432
	ds_read_b128 v[244:247], v205 offset:59328
	s_waitcnt lgkmcnt(2)
	v_mfma_f32_16x16x32_bf16 v[112:115], v[144:147], v[140:143], v[112:115]
	v_mfma_f32_16x16x32_bf16 v[80:83], v[144:147], v[134:137], v[80:83]
	ds_read_b128 v[144:147], v205 offset:50880
	s_waitcnt lgkmcnt(2)
	v_mfma_f32_16x16x32_bf16 v[100:103], v[248:251], v[140:143], v[100:103]
	v_mfma_f32_16x16x32_bf16 v[68:71], v[248:251], v[134:137], v[68:71]
	s_waitcnt lgkmcnt(0)
	v_mfma_f32_16x16x32_bf16 v[108:111], v[144:147], v[140:143], v[108:111]
	v_mfma_f32_16x16x32_bf16 v[76:79], v[144:147], v[134:137], v[76:79]
	v_mfma_f32_16x16x32_bf16 v[104:107], v[244:247], v[140:143], v[104:107]
	v_mfma_f32_16x16x32_bf16 v[72:75], v[244:247], v[134:137], v[72:75]
	v_mov_b32_e32 v240, v132
	v_mov_b32_e32 v241, v242
	s_or_b64 exec, exec, s[10:11]
	v_cmp_lt_u32_e32 vcc, 8, v171
	s_and_saveexec_b64 s[10:11], vcc
	s_cbranch_execz .LBB0_403

; __device__ __forceinline__ void attn_item(const Params& p, unsigned char* lds, int item) {
;     ...
;             { const unsigned char* va = lds + AT_V + qi * 528 + 64 * ch + 16 * g4;
; #pragma unroll
;               for (int dt = 0; dt < 8; ++dt) { const bf16x8 a = *(const bf16x8*)(va + dt * 16 * 528);
;                   otA[dt] = __builtin_amdgcn_mfma_f32_16x16x32_bf16(a, pbA, otA[dt], 0, 0, 0); otB[dt] = __builtin_amdgcn_mfma_f32_16x16x32_bf16(a, pbB, otB[dt], 0, 0, 0); } }
.LBB0_481:
	v_sub_f32_e32 v134, v145, v132
	v_exp_f32_e32 v138, v134
	v_sub_f32_e32 v134, v146, v132
	v_exp_f32_e32 v139, v134
	v_sub_f32_e32 v134, v147, v132
	v_exp_f32_e32 v192, v134
	v_sub_f32_e32 v134, v188, v132
	v_sub_f32_e32 v2, v2, v132
	v_sub_f32_e32 v3, v3, v132
	v_sub_f32_e32 v133, v144, v132
	ds_read_b128 v[144:147], v205 offset:256
	ds_read_b128 v[248:251], v205 offset:8704
	v_exp_f32_e32 v188, v134
	v_sub_f32_e32 v134, v189, v132
	v_exp_f32_e32 v2, v2
	v_exp_f32_e32 v3, v3
	v_exp_f32_e32 v133, v133
	v_exp_f32_e32 v189, v134
	v_cvt_pk_bf16_f32 v134, v2, v3
	v_cvt_pk_bf16_f32 v135, v133, v138
	v_cvt_pk_bf16_f32 v136, v139, v192
	v_cvt_pk_bf16_f32 v137, v188, v189
	s_waitcnt lgkmcnt(1)
	v_mfma_f32_16x16x32_bf16 v[128:131], v[144:147], v[140:143], v[128:131]
	v_add_f32_e32 v183, v246, v183
	v_add_f32_e32 v183, v241, v183
	v_add_f32_e32 v183, v243, v183
	v_mfma_f32_16x16x32_bf16 v[96:99], v[144:147], v[134:137], v[96:99]
	v_add_f32_e32 v183, v244, v183
	v_add_f32_e32 v183, v245, v183
	v_add_f32_e32 v183, v247, v183
	s_waitcnt lgkmcnt(0)
	v_mfma_f32_16x16x32_bf16 v[124:127], v[248:251], v[140:143], v[124:127]
	v_add_f32_e32 v2, v2, v239
	v_add_f32_e32 v2, v3, v2
	v_add_f32_e32 v2, v133, v2
	v_mfma_f32_16x16x32_bf16 v[92:95], v[248:251], v[134:137], v[92:95]
	ds_read_b128 v[144:147], v205 offset:17152
	ds_read_b128 v[248:251], v205 offset:25600
	v_add_f32_e32 v2, v138, v2
	v_add_f32_e32 v2, v139, v2
	s_waitcnt lgkmcnt(1)
	v_mfma_f32_16x16x32_bf16 v[120:123], v[144:147], v[140:143], v[120:123]
	v_add_f32_e32 v2, v192, v2
	v_add_f32_e32 v183, v190, v183
	v_add_f32_e32 v2, v188, v2
	v_mfma_f32_16x16x32_bf16 v[88:91], v[144:147], v[134:137], v[88:91]
	v_add_f32_e32 v183, v191, v183
	v_add_f32_e32 v239, v189, v2
	s_waitcnt lgkmcnt(0)
	v_mfma_f32_16x16x32_bf16 v[116:119], v[248:251], v[140:143], v[116:119]
	v_mfma_f32_16x16x32_bf16 v[84:87], v[248:251], v[134:137], v[84:87]
	ds_read_b128 v[144:147], v205 offset:34048
	ds_read_b128 v[248:251], v205 offset:42496
	ds_read_b128 v[244:247], v205 offset:59392
	s_waitcnt lgkmcnt(2)
	v_mfma_f32_16x16x32_bf16 v[112:115], v[144:147], v[140:143], v[112:115]
	v_mfma_f32_16x16x32_bf16 v[80:83], v[144:147], v[134:137], v[80:83]
	ds_read_b128 v[144:147], v205 offset:50944
	s_waitcnt lgkmcnt(2)
	v_mfma_f32_16x16x32_bf16 v[100:103], v[248:251], v[140:143], v[100:103]
	v_mfma_f32_16x16x32_bf16 v[68:71], v[248:251], v[134:137], v[68:71]
	s_waitcnt lgkmcnt(0)
	v_mfma_f32_16x16x32_bf16 v[108:111], v[144:147], v[140:143], v[108:111]
	v_mfma_f32_16x16x32_bf16 v[76:79], v[144:147], v[134:137], v[76:79]
	v_mfma_f32_16x16x32_bf16 v[104:107], v[244:247], v[140:143], v[104:107]
	v_mfma_f32_16x16x32_bf16 v[72:75], v[244:247], v[134:137], v[72:75]
	v_mov_b32_e32 v240, v132
	v_mov_b32_e32 v241, v242
	s_or_b64 exec, exec, s[10:11]
	v_cmp_lt_u32_e32 vcc, 10, v171
	s_and_saveexec_b64 s[10:11], vcc
	s_cbranch_execz .LBB0_404

; __device__ __forceinline__ void attn_item(const Params& p, unsigned char* lds, int item) {
;     ...
;             { const unsigned char* va = lds + AT_V + qi * 528 + 64 * ch + 16 * g4;
; #pragma unroll
;               for (int dt = 0; dt < 8; ++dt) { const bf16x8 a = *(const bf16x8*)(va + dt * 16 * 528);
;                   otA[dt] = __builtin_amdgcn_mfma_f32_16x16x32_bf16(a, pbA, otA[dt], 0, 0, 0); otB[dt] = __builtin_amdgcn_mfma_f32_16x16x32_bf16(a, pbB, otB[dt], 0, 0, 0); } }
.LBB0_500:
	v_sub_f32_e32 v134, v145, v132
	v_exp_f32_e32 v138, v134
	v_sub_f32_e32 v134, v146, v132
	v_exp_f32_e32 v139, v134
	v_sub_f32_e32 v134, v147, v132
	v_exp_f32_e32 v192, v134
	v_sub_f32_e32 v134, v188, v132
	v_sub_f32_e32 v2, v2, v132
	v_sub_f32_e32 v3, v3, v132
	v_sub_f32_e32 v133, v144, v132
	ds_read_b128 v[144:147], v205 offset:320
	ds_read_b128 v[248:251], v205 offset:8768
	v_exp_f32_e32 v188, v134
	v_sub_f32_e32 v134, v189, v132
	v_exp_f32_e32 v2, v2
	v_exp_f32_e32 v3, v3
	v_exp_f32_e32 v133, v133
	v_exp_f32_e32 v189, v134
	v_cvt_pk_bf16_f32 v134, v2, v3
	v_cvt_pk_bf16_f32 v135, v133, v138
	v_cvt_pk_bf16_f32 v136, v139, v192
	v_cvt_pk_bf16_f32 v137, v188, v189
	s_waitcnt lgkmcnt(1)
	v_mfma_f32_16x16x32_bf16 v[128:131], v[144:147], v[140:143], v[128:131]
	v_add_f32_e32 v183, v246, v183
	v_add_f32_e32 v183, v241, v183
	v_add_f32_e32 v183, v243, v183
	v_mfma_f32_16x16x32_bf16 v[96:99], v[144:147], v[134:137], v[96:99]
	v_add_f32_e32 v183, v244, v183
	v_add_f32_e32 v183, v245, v183
	v_add_f32_e32 v183, v247, v183
	s_waitcnt lgkmcnt(0)
	v_mfma_f32_16x16x32_bf16 v[124:127], v[248:251], v[140:143], v[124:127]
	v_add_f32_e32 v2, v2, v239
	v_add_f32_e32 v2, v3, v2
	v_add_f32_e32 v2, v133, v2
	v_mfma_f32_16x16x32_bf16 v[92:95], v[248:251], v[134:137], v[92:95]
	ds_read_b128 v[144:147], v205 offset:17216
	ds_read_b128 v[248:251], v205 offset:25664
	v_add_f32_e32 v2, v138, v2
	v_add_f32_e32 v2, v139, v2
	s_waitcnt lgkmcnt(1)
	v_mfma_f32_16x16x32_bf16 v[120:123], v[144:147], v[140:143], v[120:123]
	v_add_f32_e32 v2, v192, v2
	v_add_f32_e32 v183, v190, v183
	v_add_f32_e32 v2, v188, v2
	v_mfma_f32_16x16x32_bf16 v[88:91], v[144:147], v[134:137], v[88:91]
	v_add_f32_e32 v183, v191, v183
	v_add_f32_e32 v239, v189, v2
	s_waitcnt lgkmcnt(0)
	v_mfma_f32_16x16x32_bf16 v[116:119], v[248:251], v[140:143], v[116:119]
	v_mfma_f32_16x16x32_bf16 v[84:87], v[248:251], v[134:137], v[84:87]
	ds_read_b128 v[144:147], v205 offset:34112
	ds_read_b128 v[248:251], v205 offset:42560
	ds_read_b128 v[244:247], v205 offset:59456
	s_waitcnt lgkmcnt(2)
	v_mfma_f32_16x16x32_bf16 v[112:115], v[144:147], v[140:143], v[112:115]
	v_mfma_f32_16x16x32_bf16 v[80:83], v[144:147], v[134:137], v[80:83]
	ds_read_b128 v[144:147], v205 offset:51008
	s_waitcnt lgkmcnt(2)
	v_mfma_f32_16x16x32_bf16 v[100:103], v[248:251], v[140:143], v[100:103]
	v_mfma_f32_16x16x32_bf16 v[68:71], v[248:251], v[134:137], v[68:71]
	s_waitcnt lgkmcnt(0)
	v_mfma_f32_16x16x32_bf16 v[108:111], v[144:147], v[140:143], v[108:111]
	v_mfma_f32_16x16x32_bf16 v[76:79], v[144:147], v[134:137], v[76:79]
	v_mfma_f32_16x16x32_bf16 v[104:107], v[244:247], v[140:143], v[104:107]
	v_mfma_f32_16x16x32_bf16 v[72:75], v[244:247], v[134:137], v[72:75]
	v_mov_b32_e32 v240, v132
	v_mov_b32_e32 v241, v242
	s_or_b64 exec, exec, s[10:11]
	v_cmp_lt_u32_e32 vcc, 12, v171
	s_and_saveexec_b64 s[10:11], vcc
	s_cbranch_execz .LBB0_405

; __device__ __forceinline__ void attn_item(const Params& p, unsigned char* lds, int item) {
;     ...
;             { const unsigned char* va = lds + AT_V + qi * 528 + 64 * ch + 16 * g4;
; #pragma unroll
;               for (int dt = 0; dt < 8; ++dt) { const bf16x8 a = *(const bf16x8*)(va + dt * 16 * 528);
;                   otA[dt] = __builtin_amdgcn_mfma_f32_16x16x32_bf16(a, pbA, otA[dt], 0, 0, 0); otB[dt] = __builtin_amdgcn_mfma_f32_16x16x32_bf16(a, pbB, otB[dt], 0, 0, 0); } }
.LBB0_519:
	v_sub_f32_e32 v134, v145, v132
	v_exp_f32_e32 v138, v134
	v_sub_f32_e32 v134, v146, v132
	v_exp_f32_e32 v139, v134
	v_sub_f32_e32 v134, v147, v132
	v_exp_f32_e32 v192, v134
	v_sub_f32_e32 v134, v188, v132
	v_sub_f32_e32 v2, v2, v132
	v_sub_f32_e32 v3, v3, v132
	v_sub_f32_e32 v133, v144, v132
	ds_read_b128 v[144:147], v205 offset:384
	ds_read_b128 v[248:251], v205 offset:8832
	v_exp_f32_e32 v188, v134
	v_sub_f32_e32 v134, v189, v132
	v_exp_f32_e32 v2, v2
	v_exp_f32_e32 v3, v3
	v_exp_f32_e32 v133, v133
	v_exp_f32_e32 v189, v134
	v_cvt_pk_bf16_f32 v134, v2, v3
	v_cvt_pk_bf16_f32 v135, v133, v138
	v_cvt_pk_bf16_f32 v136, v139, v192
	v_cvt_pk_bf16_f32 v137, v188, v189
	s_waitcnt lgkmcnt(1)
	v_mfma_f32_16x16x32_bf16 v[128:131], v[144:147], v[140:143], v[128:131]
	v_add_f32_e32 v183, v246, v183
	v_add_f32_e32 v183, v241, v183
	v_add_f32_e32 v183, v243, v183
	v_mfma_f32_16x16x32_bf16 v[96:99], v[144:147], v[134:137], v[96:99]
	v_add_f32_e32 v183, v244, v183
	v_add_f32_e32 v183, v245, v183
	v_add_f32_e32 v183, v247, v183
	s_waitcnt lgkmcnt(0)
	v_mfma_f32_16x16x32_bf16 v[124:127], v[248:251], v[140:143], v[124:127]
	v_add_f32_e32 v2, v2, v239
	v_add_f32_e32 v2, v3, v2
	v_add_f32_e32 v2, v133, v2
	v_mfma_f32_16x16x32_bf16 v[92:95], v[248:251], v[134:137], v[92:95]
	ds_read_b128 v[144:147], v205 offset:17280
	ds_read_b128 v[248:251], v205 offset:25728
	v_add_f32_e32 v2, v138, v2
	v_add_f32_e32 v2, v139, v2
	s_waitcnt lgkmcnt(1)
	v_mfma_f32_16x16x32_bf16 v[120:123], v[144:147], v[140:143], v[120:123]
	v_add_f32_e32 v2, v192, v2
	v_add_f32_e32 v183, v190, v183
	v_add_f32_e32 v2, v188, v2
	v_mfma_f32_16x16x32_bf16 v[88:91], v[144:147], v[134:137], v[88:91]
	v_add_f32_e32 v183, v191, v183
	v_add_f32_e32 v239, v189, v2
	s_waitcnt lgkmcnt(0)
	v_mfma_f32_16x16x32_bf16 v[116:119], v[248:251], v[140:143], v[116:119]
	v_mfma_f32_16x16x32_bf16 v[84:87], v[248:251], v[134:137], v[84:87]
	ds_read_b128 v[144:147], v205 offset:34176
	ds_read_b128 v[248:251], v205 offset:42624
	ds_read_b128 v[244:247], v205 offset:59520
	s_waitcnt lgkmcnt(2)
	v_mfma_f32_16x16x32_bf16 v[112:115], v[144:147], v[140:143], v[112:115]
	v_mfma_f32_16x16x32_bf16 v[80:83], v[144:147], v[134:137], v[80:83]
	ds_read_b128 v[144:147], v205 offset:51072
	s_waitcnt lgkmcnt(2)
	v_mfma_f32_16x16x32_bf16 v[100:103], v[248:251], v[140:143], v[100:103]
	v_mfma_f32_16x16x32_bf16 v[68:71], v[248:251], v[134:137], v[68:71]
	s_waitcnt lgkmcnt(0)
	v_mfma_f32_16x16x32_bf16 v[108:111], v[144:147], v[140:143], v[108:111]
	v_mfma_f32_16x16x32_bf16 v[76:79], v[144:147], v[134:137], v[76:79]
	v_mfma_f32_16x16x32_bf16 v[104:107], v[244:247], v[140:143], v[104:107]
	v_mfma_f32_16x16x32_bf16 v[72:75], v[244:247], v[134:137], v[72:75]
	v_mov_b32_e32 v240, v132
	v_mov_b32_e32 v241, v242
	s_or_b64 exec, exec, s[10:11]
	v_cmp_lt_u32_e32 vcc, 14, v171
	s_and_saveexec_b64 s[88:89], vcc
	s_cbranch_execz .LBB0_539

; __device__ __forceinline__ void attn_item(const Params& p, unsigned char* lds, int item) {
;     ...
;             { const unsigned char* va = lds + AT_V + qi * 528 + 64 * ch + 16 * g4;
; #pragma unroll
;               for (int dt = 0; dt < 8; ++dt) { const bf16x8 a = *(const bf16x8*)(va + dt * 16 * 528);
;                   otA[dt] = __builtin_amdgcn_mfma_f32_16x16x32_bf16(a, pbA, otA[dt], 0, 0, 0); otB[dt] = __builtin_amdgcn_mfma_f32_16x16x32_bf16(a, pbB, otB[dt], 0, 0, 0); } }
.LBB0_538:
	ds_read_b128 v[58:61], v205 offset:448
	ds_read_b128 v[62:65], v205 offset:8896
	v_sub_f32_e32 v44, v44, v36
	v_sub_f32_e32 v37, v48, v36
	v_sub_f32_e32 v38, v49, v36
	v_sub_f32_e32 v39, v46, v36
	v_sub_f32_e32 v46, v47, v36
	v_exp_f32_e32 v49, v44
	v_sub_f32_e32 v44, v45, v36
	v_sub_f32_e32 v2, v2, v36
	v_sub_f32_e32 v3, v3, v36
	v_exp_f32_e32 v37, v37
	v_exp_f32_e32 v38, v38
	v_exp_f32_e32 v39, v39
	v_exp_f32_e32 v48, v46
	v_exp_f32_e32 v66, v44
	v_exp_f32_e32 v2, v2
	v_exp_f32_e32 v3, v3
	v_cvt_pk_bf16_f32 v44, v37, v38
	v_cvt_pk_bf16_f32 v45, v39, v48
	v_cvt_pk_bf16_f32 v46, v49, v66
	v_cvt_pk_bf16_f32 v47, v2, v3
	s_waitcnt lgkmcnt(1)
	v_mfma_f32_16x16x32_bf16 v[128:131], v[58:61], v[40:43], v[128:131]
	v_add_f32_e32 v56, v56, v183
	v_add_f32_e32 v50, v50, v56
	v_add_f32_e32 v50, v52, v50
	v_mfma_f32_16x16x32_bf16 v[96:99], v[58:61], v[44:47], v[96:99]
	v_add_f32_e32 v50, v54, v50
	v_add_f32_e32 v50, v55, v50
	v_add_f32_e32 v50, v57, v50
	s_waitcnt lgkmcnt(0)
	v_mfma_f32_16x16x32_bf16 v[124:127], v[62:65], v[40:43], v[124:127]
	v_add_f32_e32 v37, v37, v239
	v_add_f32_e32 v37, v38, v37
	v_add_f32_e32 v37, v39, v37
	v_mfma_f32_16x16x32_bf16 v[92:95], v[62:65], v[44:47], v[92:95]
	ds_read_b128 v[58:61], v205 offset:17344
	ds_read_b128 v[62:65], v205 offset:25792
	v_add_f32_e32 v37, v48, v37
	v_add_f32_e32 v37, v49, v37
	s_waitcnt lgkmcnt(1)
	v_mfma_f32_16x16x32_bf16 v[120:123], v[58:61], v[40:43], v[120:123]
	v_add_f32_e32 v37, v66, v37
	v_add_f32_e32 v50, v51, v50
	v_add_f32_e32 v2, v2, v37
	v_mfma_f32_16x16x32_bf16 v[88:91], v[58:61], v[44:47], v[88:91]
	v_add_f32_e32 v183, v53, v50
	v_add_f32_e32 v239, v3, v2
	s_waitcnt lgkmcnt(0)
	v_mfma_f32_16x16x32_bf16 v[116:119], v[62:65], v[40:43], v[116:119]
	v_mfma_f32_16x16x32_bf16 v[84:87], v[62:65], v[44:47], v[84:87]
	ds_read_b128 v[58:61], v205 offset:34240
	ds_read_b128 v[62:65], v205 offset:42688
	ds_read_b128 v[54:57], v205 offset:59584
	s_waitcnt lgkmcnt(2)
	v_mfma_f32_16x16x32_bf16 v[112:115], v[58:61], v[40:43], v[112:115]
	v_mfma_f32_16x16x32_bf16 v[80:83], v[58:61], v[44:47], v[80:83]
	ds_read_b128 v[58:61], v205 offset:51136
	s_waitcnt lgkmcnt(2)
	v_mfma_f32_16x16x32_bf16 v[100:103], v[62:65], v[40:43], v[100:103]
	v_mfma_f32_16x16x32_bf16 v[68:71], v[62:65], v[44:47], v[68:71]
	s_waitcnt lgkmcnt(0)
	v_mfma_f32_16x16x32_bf16 v[108:111], v[58:61], v[40:43], v[108:111]
	v_mfma_f32_16x16x32_bf16 v[76:79], v[58:61], v[44:47], v[76:79]
	v_mfma_f32_16x16x32_bf16 v[104:107], v[54:57], v[40:43], v[104:107]
	v_mfma_f32_16x16x32_bf16 v[72:75], v[54:57], v[44:47], v[72:75]
	v_mov_b32_e32 v240, v36
	v_mov_b32_e32 v241, v0
